# v22 + prompt-MLA loop: lazy-rescale wave-uniform test shortened to v_cmp/s_cmp/s_cbranch_scc0 (3 branches and s_cselect/s_andn2 removed) and two no-op canonicalising v_max after the permlane swap drop
# speedup vs baseline: 1.0056x; 1.0056x over previous
;     constexpr int NS = MODE == 0 ? 6 : 4, KSTR = MODE == 0 ? 208 : 144;
;     const LAS unsigned char* kb = buf + r * KSTR + hi * 16;
; #pragma unroll
;     for (int s = 0; s < NS; ++s) { const bf16x8 a0 = *(const LAS bf16x8*)(kb + 32 * s), a1 = *(const LAS bf16x8*)(kb + 32 * KSTR + 32 * s);
;         if (s == 0) { s0 = MFMA32(a0, qf[0], negm); s1 = MFMA32(a1, qf[0], negm); }
;         else { s0 = MFMA32(a0, qf[s], s0); s1 = MFMA32(a1, qf[s], s1); } }
; }
; template <int MODE> __device__ __forceinline__ void st_sm(int T, int tq, int qpos, int hi, const LAS float* biasl, f32x16& s0, f32x16& s1, f32x16& o0, f32x16& o1, f32x16& negm, float& lrun, bool& fresh) {
;     const float c2 = 0.125f * LOG2E;
;     if (MODE == 1) {
;         if (T + 5 <= tq) { const float cb = biasl[0];
; #pragma unroll
;             for (int i = 0; i < 16; ++i) { s0[i] = s0[i] * c2 + cb; s1[i] = s1[i] * c2 + cb; } }
;         else if (T + 3 >= tq) { const volatile LAS float* bp = biasl + (256 - qpos + T * 64 + 4 * hi);
; #pragma unroll
;             for (int i = 0; i < 16; ++i) { s0[i] = s0[i] * c2 + bp[(i & 3) + 8 * (i >> 2)]; s1[i] = s1[i] * c2 + bp[(i & 3) + 8 * (i >> 2) + 32]; } }
;         else {
; #pragma unroll
;             for (int i = 0; i < 16; ++i) { const int d0 = qpos - (T * 64 + crow(i, hi)); const int i0 = 256 - min(max(d0, -63), 256), i1 = 256 - min(max(d0 - 32, -63), 256);
;                 s0[i] = s0[i] * c2 + biasl[i0]; s1[i] = s1[i] * c2 + biasl[i1]; } }
;     }
;     ...
;     float ma = MX3_(s0[0], s0[1], s1[0]), mb = MX3_(s0[2], s0[3], s1[1]); ma = MX3_(ma, s1[2], s1[3]);
; #pragma unroll
;     for (int i = 4; i < 16; i += 4) { ma = MX3_(ma, s0[i], s0[i + 1]); mb = MX3_(mb, s0[i + 2], s0[i + 3]); ma = MX3_(ma, s1[i], s1[i + 1]); mb = MX3_(mb, s1[i + 2], s1[i + 3]); }
;     ...
;     float mx = halves_max(__builtin_fmaxf(ma, mb));
;     if (fresh || __any(mx > 6.0f)) {
;         const float dl = fresh ? mx : fmaxf(mx, 0.f), al = __builtin_amdgcn_exp2f(-dl); lrun *= al; fresh = false;
;         const float dn = (MODE == 0) ? dl : dl * (8.0f / LOG2E);
; #pragma unroll
;         for (int i = 0; i < 16; ++i) { s0[i] -= dl; s1[i] -= dl; o0[i] *= al; o1[i] *= al; negm[i] -= dn; } }
;     float sum = 0.f;
; #pragma unroll
;     for (int i = 0; i < 16; ++i) { s0[i] = __builtin_amdgcn_exp2f(s0[i]); s1[i] = __builtin_amdgcn_exp2f(s1[i]); sum += s0[i] + s1[i]; }
;     lrun += sum;
; }
.LBB0_666:
	s_add_i32 s0, s11, 1
	s_min_i32 s6, s0, s3
	s_waitcnt vmcnt(2)
	v_mad_i64_i32 v[4:5], s[0:1], v170, s6, v[180:181]
	s_waitcnt vmcnt(1)
	v_mad_i64_i32 v[8:9], s[0:1], v172, s6, v[178:179]
	s_waitcnt vmcnt(0)
	v_mad_i64_i32 v[12:13], s[0:1], v174, s6, v[176:177]
	global_load_dwordx4 v[4:7], v[4:5], off
	s_add_i32 s13, s11, -1
	global_load_dwordx4 v[8:11], v[8:9], off
	s_cmp_le_i32 s13, s10
	global_load_dwordx4 v[12:15], v[12:13], off
	s_cselect_b64 s[0:1], -1, 0
	s_and_b64 s[0:1], s[8:9], s[0:1]
	s_andn2_b64 vcc, exec, s[0:1]
	s_cbranch_vccnz .LBB0_674
	v_add_u32_e32 v2, v171, v168
	s_xor_b64 s[0:1], s[4:5], -1
	s_and_b64 vcc, exec, s[0:1]
	ds_read_b128 v[66:69], v2
	ds_read_b128 v[134:137], v2 offset:6656
	ds_read_b128 v[138:141], v2 offset:32
	ds_read_b128 v[142:145], v2 offset:6688
	ds_read_b128 v[146:149], v2 offset:64
	ds_read_b128 v[150:153], v2 offset:6720
	ds_read_b128 v[154:157], v2 offset:96
	ds_read_b128 v[158:161], v2 offset:6752
	ds_read_b128 v[162:165], v2 offset:128
	s_waitcnt lgkmcnt(8)
	v_mfma_f32_32x32x16_bf16 v[82:97], v[66:69], v[110:113], v[50:65]
	s_waitcnt lgkmcnt(7)
	v_mfma_f32_32x32x16_bf16 v[66:81], v[134:137], v[110:113], v[50:65]
	ds_read_b128 v[134:137], v2 offset:6784
	s_waitcnt lgkmcnt(7)
	v_mfma_f32_32x32x16_bf16 v[82:97], v[138:141], v[106:109], v[82:97]
	ds_read_b128 v[138:141], v2 offset:160
	s_waitcnt lgkmcnt(7)
	v_mfma_f32_32x32x16_bf16 v[66:81], v[142:145], v[106:109], v[66:81]
	ds_read_b128 v[142:145], v2 offset:6816
	v_add_u32_e32 v2, 0x100, v183
	s_waitcnt lgkmcnt(7)
	v_mfma_f32_32x32x16_bf16 v[82:97], v[146:149], v[102:105], v[82:97]
	s_waitcnt lgkmcnt(6)
	v_mfma_f32_32x32x16_bf16 v[66:81], v[150:153], v[102:105], v[66:81]
	s_waitcnt lgkmcnt(5)
	v_mfma_f32_32x32x16_bf16 v[82:97], v[154:157], v[98:101], v[82:97]
	s_waitcnt lgkmcnt(4)
	v_mfma_f32_32x32x16_bf16 v[66:81], v[158:161], v[98:101], v[66:81]
	s_waitcnt lgkmcnt(3)
	v_mfma_f32_32x32x16_bf16 v[82:97], v[162:165], v[118:121], v[82:97]
	s_waitcnt lgkmcnt(2)
	v_mfma_f32_32x32x16_bf16 v[66:81], v[134:137], v[118:121], v[66:81]
	s_waitcnt lgkmcnt(1)
	v_mfma_f32_32x32x16_bf16 v[82:97], v[138:141], v[114:117], v[82:97]
	s_waitcnt lgkmcnt(0)
	v_mfma_f32_32x32x16_bf16 v[66:81], v[142:145], v[114:117], v[66:81]
	ds_read_b64_tr_b16 v[162:163], v2 offset:13312
	ds_read_b64_tr_b16 v[164:165], v2 offset:14848
	ds_read_b64_tr_b16 v[158:159], v2 offset:13376
	ds_read_b64_tr_b16 v[160:161], v2 offset:14912
	ds_read_b64_tr_b16 v[150:151], v2 offset:16384
	ds_read_b64_tr_b16 v[152:153], v2 offset:17920
	ds_read_b64_tr_b16 v[154:155], v2 offset:16448
	ds_read_b64_tr_b16 v[156:157], v2 offset:17984
	ds_read_b64_tr_b16 v[146:147], v2 offset:19456
	ds_read_b64_tr_b16 v[148:149], v2 offset:20992
	ds_read_b64_tr_b16 v[142:143], v2 offset:19520
	ds_read_b64_tr_b16 v[144:145], v2 offset:21056
	ds_read_b64_tr_b16 v[138:139], v2 offset:22528
	ds_read_b64_tr_b16 v[140:141], v2 offset:24064
	ds_read_b64_tr_b16 v[134:135], v2 offset:22592
	ds_read_b64_tr_b16 v[136:137], v2 offset:24128
	v_max_f32_e32 v2, v83, v83
	v_max_f32_e32 v16, v82, v82
	v_max_f32_e32 v2, v16, v2
	v_max3_f32 v16, v84, v85, v67
	v_max3_f32 v2, v2, v66, v68
	v_max3_f32 v2, v2, v69, v86
	v_max3_f32 v16, v16, v88, v89
	v_max3_f32 v2, v2, v87, v70
	v_max3_f32 v16, v16, v72, v73
	v_max3_f32 v2, v2, v71, v90
	v_max3_f32 v16, v16, v92, v93
	v_max3_f32 v2, v2, v91, v74
	v_max3_f32 v16, v16, v76, v77
	v_max3_f32 v2, v2, v75, v94
	v_max3_f32 v16, v16, v96, v97
	v_max3_f32 v2, v2, v95, v78
	v_max3_f32 v16, v16, v80, v81
	v_max3_f32 v2, v2, v79, v16
	v_mov_b32_e32 v16, v2
	s_nop 1
	v_permlane32_swap_b32_e32 v2, v16
	v_max_f32_e32 v2, v2, v16
	s_cbranch_vccz .Lrs0
	v_cmp_lt_f32_e32 vcc, s58, v2
	s_cmp_lg_u64 vcc, 0
	s_cbranch_scc0 .LBB0_673
.Lrs0:
	v_max_f32_e32 v16, v2, v2
	v_max_f32_e32 v16, 0, v16
	v_cndmask_b32_e64 v2, v16, v2, s[4:5]
	v_exp_f32_e64 v16, -v2
	v_pk_add_f32 v[82:83], v[82:83], v[2:3] op_sel_hi:[1,0] neg_lo:[0,1] neg_hi:[0,1]
	v_pk_add_f32 v[66:67], v[66:67], v[2:3] op_sel_hi:[1,0] neg_lo:[0,1] neg_hi:[0,1]
	v_pk_add_f32 v[84:85], v[84:85], v[2:3] op_sel_hi:[1,0] neg_lo:[0,1] neg_hi:[0,1]
	v_mul_f32_e32 v167, v167, v16
	v_pk_add_f32 v[68:69], v[68:69], v[2:3] op_sel_hi:[1,0] neg_lo:[0,1] neg_hi:[0,1]
	v_pk_add_f32 v[86:87], v[86:87], v[2:3] op_sel_hi:[1,0] neg_lo:[0,1] neg_hi:[0,1]
	v_pk_add_f32 v[70:71], v[70:71], v[2:3] op_sel_hi:[1,0] neg_lo:[0,1] neg_hi:[0,1]
	v_pk_add_f32 v[88:89], v[88:89], v[2:3] op_sel_hi:[1,0] neg_lo:[0,1] neg_hi:[0,1]
	v_pk_add_f32 v[72:73], v[72:73], v[2:3] op_sel_hi:[1,0] neg_lo:[0,1] neg_hi:[0,1]
	v_pk_add_f32 v[90:91], v[90:91], v[2:3] op_sel_hi:[1,0] neg_lo:[0,1] neg_hi:[0,1]
	v_pk_add_f32 v[74:75], v[74:75], v[2:3] op_sel_hi:[1,0] neg_lo:[0,1] neg_hi:[0,1]
	v_pk_add_f32 v[92:93], v[92:93], v[2:3] op_sel_hi:[1,0] neg_lo:[0,1] neg_hi:[0,1]
	v_pk_add_f32 v[76:77], v[76:77], v[2:3] op_sel_hi:[1,0] neg_lo:[0,1] neg_hi:[0,1]
	v_pk_add_f32 v[94:95], v[94:95], v[2:3] op_sel_hi:[1,0] neg_lo:[0,1] neg_hi:[0,1]
	v_pk_add_f32 v[78:79], v[78:79], v[2:3] op_sel_hi:[1,0] neg_lo:[0,1] neg_hi:[0,1]
	v_pk_add_f32 v[96:97], v[96:97], v[2:3] op_sel_hi:[1,0] neg_lo:[0,1] neg_hi:[0,1]
	v_pk_add_f32 v[80:81], v[80:81], v[2:3] op_sel_hi:[1,0] neg_lo:[0,1] neg_hi:[0,1]
	v_pk_mul_f32 v[48:49], v[48:49], v[16:17] op_sel_hi:[1,0]
	v_pk_mul_f32 v[46:47], v[46:47], v[16:17] op_sel_hi:[1,0]
	v_pk_mul_f32 v[44:45], v[44:45], v[16:17] op_sel_hi:[1,0]
	v_pk_mul_f32 v[42:43], v[42:43], v[16:17] op_sel_hi:[1,0]
	v_pk_mul_f32 v[40:41], v[40:41], v[16:17] op_sel_hi:[1,0]
	v_pk_mul_f32 v[38:39], v[38:39], v[16:17] op_sel_hi:[1,0]
	v_pk_mul_f32 v[36:37], v[36:37], v[16:17] op_sel_hi:[1,0]
	v_pk_mul_f32 v[34:35], v[34:35], v[16:17] op_sel_hi:[1,0]
	v_pk_mul_f32 v[32:33], v[32:33], v[16:17] op_sel_hi:[1,0]
	v_pk_mul_f32 v[30:31], v[30:31], v[16:17] op_sel_hi:[1,0]
	v_pk_mul_f32 v[28:29], v[28:29], v[16:17] op_sel_hi:[1,0]
	v_pk_mul_f32 v[26:27], v[26:27], v[16:17] op_sel_hi:[1,0]
	v_pk_mul_f32 v[24:25], v[24:25], v[16:17] op_sel_hi:[1,0]
	v_pk_mul_f32 v[22:23], v[22:23], v[16:17] op_sel_hi:[1,0]
	v_pk_mul_f32 v[20:21], v[20:21], v[16:17] op_sel_hi:[1,0]
	v_pk_mul_f32 v[18:19], v[18:19], v[16:17] op_sel_hi:[1,0]
	v_sub_f32_e32 v65, v65, v2
	v_sub_f32_e32 v64, v64, v2
	v_sub_f32_e32 v63, v63, v2
	v_sub_f32_e32 v62, v62, v2
	v_sub_f32_e32 v61, v61, v2
	v_sub_f32_e32 v60, v60, v2
	v_sub_f32_e32 v59, v59, v2
	v_sub_f32_e32 v58, v58, v2
	v_sub_f32_e32 v57, v57, v2
	v_sub_f32_e32 v56, v56, v2
	v_sub_f32_e32 v55, v55, v2
	v_sub_f32_e32 v54, v54, v2
	v_sub_f32_e32 v53, v53, v2
	v_sub_f32_e32 v52, v52, v2
	v_sub_f32_e32 v51, v51, v2
	v_sub_f32_e32 v50, v50, v2

;     constexpr int NS = MODE == 0 ? 6 : 4, KSTR = MODE == 0 ? 208 : 144;
;     const LAS unsigned char* kb = buf + r * KSTR + hi * 16;
; #pragma unroll
;     for (int s = 0; s < NS; ++s) { const bf16x8 a0 = *(const LAS bf16x8*)(kb + 32 * s), a1 = *(const LAS bf16x8*)(kb + 32 * KSTR + 32 * s);
;         if (s == 0) { s0 = MFMA32(a0, qf[0], negm); s1 = MFMA32(a1, qf[0], negm); }
;         else { s0 = MFMA32(a0, qf[s], s0); s1 = MFMA32(a1, qf[s], s1); } }
; }
; template <int MODE> __device__ __forceinline__ void st_sm(int T, int tq, int qpos, int hi, const LAS float* biasl, f32x16& s0, f32x16& s1, f32x16& o0, f32x16& o1, f32x16& negm, float& lrun, bool& fresh) {
;     const float c2 = 0.125f * LOG2E;
;     if (MODE == 1) {
;         if (T + 5 <= tq) { const float cb = biasl[0];
; #pragma unroll
;             for (int i = 0; i < 16; ++i) { s0[i] = s0[i] * c2 + cb; s1[i] = s1[i] * c2 + cb; } }
;         else if (T + 3 >= tq) { const volatile LAS float* bp = biasl + (256 - qpos + T * 64 + 4 * hi);
; #pragma unroll
;             for (int i = 0; i < 16; ++i) { s0[i] = s0[i] * c2 + bp[(i & 3) + 8 * (i >> 2)]; s1[i] = s1[i] * c2 + bp[(i & 3) + 8 * (i >> 2) + 32]; } }
;         else {
; #pragma unroll
;             for (int i = 0; i < 16; ++i) { const int d0 = qpos - (T * 64 + crow(i, hi)); const int i0 = 256 - min(max(d0, -63), 256), i1 = 256 - min(max(d0 - 32, -63), 256);
;                 s0[i] = s0[i] * c2 + biasl[i0]; s1[i] = s1[i] * c2 + biasl[i1]; } }
;     }
;     ...
;     float ma = MX3_(s0[0], s0[1], s1[0]), mb = MX3_(s0[2], s0[3], s1[1]); ma = MX3_(ma, s1[2], s1[3]);
; #pragma unroll
;     for (int i = 4; i < 16; i += 4) { ma = MX3_(ma, s0[i], s0[i + 1]); mb = MX3_(mb, s0[i + 2], s0[i + 3]); ma = MX3_(ma, s1[i], s1[i + 1]); mb = MX3_(mb, s1[i + 2], s1[i + 3]); }
;     ...
;     float mx = halves_max(__builtin_fmaxf(ma, mb));
;     if (fresh || __any(mx > 6.0f)) {
;         const float dl = fresh ? mx : fmaxf(mx, 0.f), al = __builtin_amdgcn_exp2f(-dl); lrun *= al; fresh = false;
;         const float dn = (MODE == 0) ? dl : dl * (8.0f / LOG2E);
; #pragma unroll
;         for (int i = 0; i < 16; ++i) { s0[i] -= dl; s1[i] -= dl; o0[i] *= al; o1[i] *= al; negm[i] -= dn; } }
;     float sum = 0.f;
; #pragma unroll
;     for (int i = 0; i < 16; ++i) { s0[i] = __builtin_amdgcn_exp2f(s0[i]); s1[i] = __builtin_amdgcn_exp2f(s1[i]); sum += s0[i] + s1[i]; }
;     lrun += sum;
; }
.LBB0_676:
	s_waitcnt lgkmcnt(0)
	s_barrier
	s_andn2_b64 vcc, exec, s[0:1]
	s_mov_b64 s[0:1], -1
	s_cbranch_vccnz .LBB0_680
	s_add_i32 s12, s11, 2
	s_min_i32 s6, s12, s3
	v_mad_i64_i32 v[16:17], s[0:1], v170, s6, v[180:181]
	global_load_dwordx4 v[122:125], v[16:17], off
	v_mad_i64_i32 v[16:17], s[0:1], v172, s6, v[178:179]
	global_load_dwordx4 v[126:129], v[16:17], off
	v_mad_i64_i32 v[16:17], s[0:1], v174, s6, v[176:177]
	global_load_dwordx4 v[130:133], v[16:17], off
	s_cmp_lt_i32 s13, s10
	s_cselect_b64 s[0:1], -1, 0
	s_and_b64 s[0:1], s[8:9], s[0:1]
	s_andn2_b64 vcc, exec, s[0:1]
	s_cbranch_vccnz .LBB0_686
	v_add_u32_e32 v2, v171, v168
	s_xor_b64 s[0:1], s[4:5], -1
	s_and_b64 vcc, exec, s[0:1]
	ds_read_b128 v[66:69], v2 offset:25600
	ds_read_b128 v[134:137], v2 offset:32256
	ds_read_b128 v[138:141], v2 offset:25632
	ds_read_b128 v[142:145], v2 offset:32288
	ds_read_b128 v[146:149], v2 offset:25664
	ds_read_b128 v[150:153], v2 offset:32320
	ds_read_b128 v[154:157], v2 offset:25696
	ds_read_b128 v[158:161], v2 offset:32352
	ds_read_b128 v[162:165], v2 offset:25728
	s_waitcnt lgkmcnt(8)
	v_mfma_f32_32x32x16_bf16 v[82:97], v[66:69], v[110:113], v[50:65]
	s_waitcnt lgkmcnt(7)
	v_mfma_f32_32x32x16_bf16 v[66:81], v[134:137], v[110:113], v[50:65]
	ds_read_b128 v[134:137], v2 offset:32384
	s_waitcnt lgkmcnt(7)
	v_mfma_f32_32x32x16_bf16 v[82:97], v[138:141], v[106:109], v[82:97]
	ds_read_b128 v[138:141], v2 offset:25760
	s_waitcnt lgkmcnt(7)
	v_mfma_f32_32x32x16_bf16 v[66:81], v[142:145], v[106:109], v[66:81]
	ds_read_b128 v[142:145], v2 offset:32416
	v_add_u32_e32 v2, 0x100, v183
	s_waitcnt lgkmcnt(7)
	v_mfma_f32_32x32x16_bf16 v[82:97], v[146:149], v[102:105], v[82:97]
	s_waitcnt lgkmcnt(6)
	v_mfma_f32_32x32x16_bf16 v[66:81], v[150:153], v[102:105], v[66:81]
	s_waitcnt lgkmcnt(5)
	v_mfma_f32_32x32x16_bf16 v[82:97], v[154:157], v[98:101], v[82:97]
	s_waitcnt lgkmcnt(4)
	v_mfma_f32_32x32x16_bf16 v[66:81], v[158:161], v[98:101], v[66:81]
	s_waitcnt lgkmcnt(3)
	v_mfma_f32_32x32x16_bf16 v[82:97], v[162:165], v[118:121], v[82:97]
	s_waitcnt lgkmcnt(2)
	v_mfma_f32_32x32x16_bf16 v[66:81], v[134:137], v[118:121], v[66:81]
	s_waitcnt lgkmcnt(1)
	v_mfma_f32_32x32x16_bf16 v[82:97], v[138:141], v[114:117], v[82:97]
	s_waitcnt lgkmcnt(0)
	v_mfma_f32_32x32x16_bf16 v[66:81], v[142:145], v[114:117], v[66:81]
	ds_read_b64_tr_b16 v[162:163], v2 offset:38912
	ds_read_b64_tr_b16 v[164:165], v2 offset:40448
	ds_read_b64_tr_b16 v[158:159], v2 offset:38976
	ds_read_b64_tr_b16 v[160:161], v2 offset:40512
	ds_read_b64_tr_b16 v[150:151], v2 offset:41984
	ds_read_b64_tr_b16 v[152:153], v2 offset:43520
	ds_read_b64_tr_b16 v[154:155], v2 offset:42048
	ds_read_b64_tr_b16 v[156:157], v2 offset:43584
	ds_read_b64_tr_b16 v[146:147], v2 offset:45056
	ds_read_b64_tr_b16 v[148:149], v2 offset:46592
	ds_read_b64_tr_b16 v[142:143], v2 offset:45120
	ds_read_b64_tr_b16 v[144:145], v2 offset:46656
	ds_read_b64_tr_b16 v[138:139], v2 offset:48128
	ds_read_b64_tr_b16 v[140:141], v2 offset:49664
	ds_read_b64_tr_b16 v[134:135], v2 offset:48192
	ds_read_b64_tr_b16 v[136:137], v2 offset:49728
	v_max_f32_e32 v2, v83, v83
	v_max_f32_e32 v16, v82, v82
	v_max_f32_e32 v2, v16, v2
	v_max3_f32 v16, v84, v85, v67
	v_max3_f32 v2, v2, v66, v68
	v_max3_f32 v2, v2, v69, v86
	v_max3_f32 v16, v16, v88, v89
	v_max3_f32 v2, v2, v87, v70
	v_max3_f32 v16, v16, v72, v73
	v_max3_f32 v2, v2, v71, v90
	v_max3_f32 v16, v16, v92, v93
	v_max3_f32 v2, v2, v91, v74
	v_max3_f32 v16, v16, v76, v77
	v_max3_f32 v2, v2, v75, v94
	v_max3_f32 v16, v16, v96, v97
	v_max3_f32 v2, v2, v95, v78
	v_max3_f32 v16, v16, v80, v81
	v_max3_f32 v2, v2, v79, v16
	v_mov_b32_e32 v16, v2
	s_nop 1
	v_permlane32_swap_b32_e32 v2, v16
	v_max_f32_e32 v2, v2, v16
	s_cbranch_vccz .Lrs1
	v_cmp_lt_f32_e32 vcc, s58, v2
	s_cmp_lg_u64 vcc, 0
	s_cbranch_scc0 .LBB0_685
	s_branch .Lrs1
